# phase2 GEMM: hoisted prefetch loads, LDS writes interleaved with MFMAs, hand-written bf16 store epilogue
# speedup vs baseline: 1.0139x; 1.0139x over previous
; #define GLOAD(kt) do { const int ko = (kt) * BK; \
;     ra0 = *(const uint4*)(gA + ko); ra1 = *(const uint4*)(gA + sA + ko); ra2 = *(const uint4*)(gA + 2 * sA + ko); ra3 = *(const uint4*)(gA + 3 * sA + ko); \
;     rb0 = *(const uint4*)(gB + ko); rb1 = *(const uint4*)(gB + sB + ko); rb2 = *(const uint4*)(gB + 2 * sB + ko); rb3 = *(const uint4*)(gB + 3 * sB + ko); } while (0)
; #define LSTORE(st) do { \
;     *(uint4*)(lA + (st) * ASZ) = ra0; *(uint4*)(lA + (st) * ASZ + 64 * LDT) = ra1; *(uint4*)(lA + (st) * ASZ + 128 * LDT) = ra2; *(uint4*)(lA + (st) * ASZ + 192 * LDT) = ra3; \
;     *(uint4*)(lB + (st) * BSZ) = rb0; *(uint4*)(lB + (st) * BSZ + 64 * LDT) = rb1; *(uint4*)(lB + (st) * BSZ + 128 * LDT) = rb2; *(uint4*)(lB + (st) * BSZ + 192 * LDT) = rb3; } while (0)
; template <class Epi>
; DI void gemm_tile(const GemmDesc g, int m0, int n0, unsigned char* lds, Epi& epi) {
;     ...
;   __syncthreads();
;   GLOAD(0);
;   LSTORE(0);
;   __syncthreads();
;   for (int kt = 0; kt < nk; kt += 2) {
;     const bool h1 = kt + 1 < nk, h2 = kt + 2 < nk;
;     if (h1) GLOAD(kt + 1);
;     COMPUTE(0);
;     if (h1) LSTORE(1);
;     __syncthreads();
;     if (h1) {
;       if (h2) GLOAD(kt + 2);
;       COMPUTE(1);
;       if (h2) LSTORE(0);
;       __syncthreads();
.LBB0_193:
	v_lshl_add_u64 v[240:241], v[166:167], 0, v[160:161]
	v_lshl_add_u64 v[238:239], v[168:169], 0, v[160:161]
	v_add_co_u32_e32 v128, vcc, 0x5a68000, v240
	s_nop 1
	v_addc_co_u32_e32 v129, vcc, 0, v241, vcc
	global_load_dwordx4 v[128:131], v[128:129], off offset:128
	v_add_co_u32_e32 v132, vcc, 0x5a88000, v240
	s_nop 1
	v_addc_co_u32_e32 v133, vcc, 0, v241, vcc
	global_load_dwordx4 v[132:135], v[132:133], off offset:128
	v_add_co_u32_e32 v136, vcc, 0x5aa8000, v240
	s_nop 1
	v_addc_co_u32_e32 v137, vcc, 0, v241, vcc
	global_load_dwordx4 v[136:139], v[136:137], off offset:128
	v_add_co_u32_e32 v140, vcc, 0x5ac8000, v240
	s_nop 1
	v_addc_co_u32_e32 v141, vcc, 0, v241, vcc
	global_load_dwordx4 v[140:143], v[140:141], off offset:128
	v_add_co_u32_e32 v144, vcc, 0x10000, v238
	s_nop 1
	v_addc_co_u32_e32 v145, vcc, 0, v239, vcc
	global_load_dwordx4 v[144:147], v[144:145], off offset:128
	v_add_co_u32_e32 v148, vcc, 0x30000, v238
	s_nop 1
	v_addc_co_u32_e32 v149, vcc, 0, v239, vcc
	global_load_dwordx4 v[148:151], v[148:149], off offset:128
	v_add_co_u32_e32 v152, vcc, 0x50000, v238
	s_nop 1
	v_addc_co_u32_e32 v153, vcc, 0, v239, vcc
	global_load_dwordx4 v[152:155], v[152:153], off offset:128
	v_add_co_u32_e32 v156, vcc, 0x70000, v238
	s_nop 1
	v_addc_co_u32_e32 v157, vcc, 0, v239, vcc
	global_load_dwordx4 v[156:159], v[156:157], off offset:128
	ds_read_b128 v[196:199], v164
	ds_read_b128 v[200:203], v163
	ds_read_b128 v[204:207], v164 offset:32
	ds_read_b128 v[210:213], v163 offset:32
	ds_read_b128 v[214:217], v163 offset:4608
	ds_read_b128 v[218:221], v163 offset:4640
	s_waitcnt lgkmcnt(4)
	v_mfma_f32_32x32x16_bf16 v[112:127], v[196:199], v[200:203], v[112:127]
	s_cmp_lt_u32 s9, 14
	s_cselect_b64 s[6:7], -1, 0
	s_cmp_gt_u32 s9, 13
	s_waitcnt lgkmcnt(1)
	v_mfma_f32_32x32x16_bf16 v[96:111], v[196:199], v[214:217], v[96:111]
	ds_read_b128 v[196:199], v164 offset:4608
	ds_read_b128 v[222:225], v164 offset:4640
	s_waitcnt lgkmcnt(1)
	v_mfma_f32_32x32x16_bf16 v[80:95], v[196:199], v[200:203], v[80:95]
	v_mfma_f32_32x32x16_bf16 v[64:79], v[196:199], v[214:217], v[64:79]
	ds_read_b128 v[196:199], v164 offset:9216
	ds_read_b128 v[226:229], v164 offset:9248
	s_waitcnt lgkmcnt(1)
	v_mfma_f32_32x32x16_bf16 v[48:63], v[196:199], v[200:203], v[48:63]
	v_mfma_f32_32x32x16_bf16 v[32:47], v[196:199], v[214:217], v[32:47]
	ds_read_b128 v[196:199], v164 offset:13824
	ds_read_b128 v[170:173], v164 offset:13856
	s_waitcnt lgkmcnt(1)
	v_mfma_f32_32x32x16_bf16 v[16:31], v[196:199], v[200:203], v[16:31]
	v_mfma_f32_32x32x16_bf16 v[112:127], v[204:207], v[210:213], v[112:127]
	v_mfma_f32_32x32x16_bf16 v[96:111], v[204:207], v[218:221], v[96:111]
	v_mfma_f32_32x32x16_bf16 v[0:15], v[196:199], v[214:217], v[0:15]
	ds_read_b128 v[196:199], v164 offset:64
	ds_read_b128 v[200:203], v163 offset:64
	ds_read_b128 v[204:207], v164 offset:96
	ds_read_b128 v[180:183], v163 offset:96
	v_mfma_f32_32x32x16_bf16 v[80:95], v[222:225], v[210:213], v[80:95]
	v_mfma_f32_32x32x16_bf16 v[64:79], v[222:225], v[218:221], v[64:79]
	v_mfma_f32_32x32x16_bf16 v[48:63], v[226:229], v[210:213], v[48:63]
	s_waitcnt lgkmcnt(4)
	v_mfma_f32_32x32x16_bf16 v[16:31], v[170:173], v[210:213], v[16:31]
	ds_read_b128 v[210:213], v163 offset:4672
	ds_read_b128 v[184:187], v163 offset:4704
	v_mfma_f32_32x32x16_bf16 v[32:47], v[226:229], v[218:221], v[32:47]
	s_waitcnt lgkmcnt(4)
	v_mfma_f32_32x32x16_bf16 v[112:127], v[196:199], v[200:203], v[112:127]
	s_waitcnt lgkmcnt(1)
	v_mfma_f32_32x32x16_bf16 v[96:111], v[196:199], v[210:213], v[96:111]
	ds_read_b128 v[196:199], v164 offset:4672
	ds_read_b128 v[222:225], v164 offset:4704
	s_waitcnt lgkmcnt(1)
	v_mfma_f32_32x32x16_bf16 v[80:95], v[196:199], v[200:203], v[80:95]
	v_mfma_f32_32x32x16_bf16 v[64:79], v[196:199], v[210:213], v[64:79]
	ds_read_b128 v[196:199], v164 offset:9280
	ds_read_b128 v[188:191], v164 offset:9312
	v_mfma_f32_32x32x16_bf16 v[0:15], v[170:173], v[218:221], v[0:15]
	v_lshl_add_u64 v[172:173], v[166:167], 0, v[160:161]
	v_lshl_add_u64 v[170:171], v[168:169], 0, v[160:161]
	s_waitcnt lgkmcnt(1)
	v_mfma_f32_32x32x16_bf16 v[48:63], v[196:199], v[200:203], v[48:63]
	v_mfma_f32_32x32x16_bf16 v[32:47], v[196:199], v[210:213], v[32:47]
	ds_read_b128 v[196:199], v164 offset:13888
	ds_read_b128 v[192:195], v164 offset:13920
	s_cselect_b64 s[4:5], -1, 0
	s_waitcnt lgkmcnt(0)
	v_mfma_f32_32x32x16_bf16 v[16:31], v[196:199], v[200:203], v[16:31]
	v_mfma_f32_32x32x16_bf16 v[0:15], v[196:199], v[210:213], v[0:15]
	s_waitcnt vmcnt(7)
	ds_write_b128 v162, v[128:131] offset:36864
	v_mfma_f32_32x32x16_bf16 v[80:95], v[222:225], v[180:183], v[80:95]
	s_waitcnt vmcnt(6)
	ds_write_b128 v162, v[132:135] offset:46080
	v_mfma_f32_32x32x16_bf16 v[64:79], v[222:225], v[184:187], v[64:79]
	s_waitcnt vmcnt(5)
	ds_write_b128 v162, v[136:139] offset:55296
	v_mfma_f32_32x32x16_bf16 v[112:127], v[204:207], v[180:183], v[112:127]
	s_waitcnt vmcnt(4)
	ds_write_b128 v162, v[140:143] offset:64512
	v_mfma_f32_32x32x16_bf16 v[96:111], v[204:207], v[184:187], v[96:111]
	s_waitcnt vmcnt(3)
	ds_write_b128 v178, v[144:147] offset:36864
	v_mfma_f32_32x32x16_bf16 v[48:63], v[188:191], v[180:183], v[48:63]
	s_waitcnt vmcnt(2)
	ds_write_b128 v178, v[148:151] offset:46080
	v_mfma_f32_32x32x16_bf16 v[32:47], v[188:191], v[184:187], v[32:47]
	s_waitcnt vmcnt(1)
	ds_write_b128 v178, v[152:155] offset:55296
	v_mfma_f32_32x32x16_bf16 v[16:31], v[192:195], v[180:183], v[16:31]
	s_waitcnt vmcnt(0)
	ds_write_b128 v178, v[156:159] offset:64512
	v_mfma_f32_32x32x16_bf16 v[0:15], v[192:195], v[184:187], v[0:15]
	s_and_b64 vcc, exec, s[4:5]
	s_waitcnt lgkmcnt(0)
	s_barrier
	s_cbranch_vccnz .LBB0_195
	v_add_co_u32_e32 v128, vcc, 0x5a68000, v172
	s_nop 1
	v_addc_co_u32_e32 v129, vcc, 0, v173, vcc
	v_add_co_u32_e32 v132, vcc, 0x5a88000, v172
	s_nop 1
	v_addc_co_u32_e32 v133, vcc, 0, v173, vcc
	v_add_co_u32_e32 v136, vcc, 0x5aa8000, v172
	global_load_dwordx4 v[128:131], v[128:129], off offset:256
	s_nop 0
	global_load_dwordx4 v[132:135], v[132:133], off offset:256
	v_addc_co_u32_e32 v137, vcc, 0, v173, vcc
	v_add_co_u32_e32 v140, vcc, 0x5ac8000, v172
	s_nop 1
	v_addc_co_u32_e32 v141, vcc, 0, v173, vcc
	v_add_co_u32_e32 v144, vcc, 0x10000, v170
	global_load_dwordx4 v[136:139], v[136:137], off offset:256
	s_nop 0
	global_load_dwordx4 v[140:143], v[140:141], off offset:256
	v_addc_co_u32_e32 v145, vcc, 0, v171, vcc
	v_add_co_u32_e32 v148, vcc, 0x30000, v170
	s_nop 1
	v_addc_co_u32_e32 v149, vcc, 0, v171, vcc
	v_add_co_u32_e32 v152, vcc, 0x50000, v170
	global_load_dwordx4 v[144:147], v[144:145], off offset:256
	s_nop 0
	global_load_dwordx4 v[148:151], v[148:149], off offset:256
	v_addc_co_u32_e32 v153, vcc, 0, v171, vcc
	v_add_co_u32_e32 v156, vcc, 0x70000, v170
	s_nop 1
	v_addc_co_u32_e32 v157, vcc, 0, v171, vcc
	global_load_dwordx4 v[152:155], v[152:153], off offset:256
	s_nop 0
	global_load_dwordx4 v[156:159], v[156:157], off offset:256
; #define GLOAD(kt) do { const int ko = (kt) * BK; \
;     ra0 = *(const uint4*)(gA + ko); ra1 = *(const uint4*)(gA + sA + ko); ra2 = *(const uint4*)(gA + 2 * sA + ko); ra3 = *(const uint4*)(gA + 3 * sA + ko); \
;     rb0 = *(const uint4*)(gB + ko); rb1 = *(const uint4*)(gB + sB + ko); rb2 = *(const uint4*)(gB + 2 * sB + ko); rb3 = *(const uint4*)(gB + 3 * sB + ko); } while (0)
; #define LSTORE(st) do { \
;     *(uint4*)(lA + (st) * ASZ) = ra0; *(uint4*)(lA + (st) * ASZ + 64 * LDT) = ra1; *(uint4*)(lA + (st) * ASZ + 128 * LDT) = ra2; *(uint4*)(lA + (st) * ASZ + 192 * LDT) = ra3; \
;     *(uint4*)(lB + (st) * BSZ) = rb0; *(uint4*)(lB + (st) * BSZ + 64 * LDT) = rb1; *(uint4*)(lB + (st) * BSZ + 128 * LDT) = rb2; *(uint4*)(lB + (st) * BSZ + 192 * LDT) = rb3; } while (0)
; template <class Epi>
; DI void gemm_tile(const GemmDesc g, int m0, int n0, unsigned char* lds, Epi& epi) {
;     ...
;     if (h1) LSTORE(1);
;     __syncthreads();
;     if (h1) {
;       if (h2) GLOAD(kt + 2);
;       COMPUTE(1);
;       if (h2) LSTORE(0);
;       __syncthreads();
;     ...
; #pragma unroll
;   for (int i = 0; i < 4; ++i)
; #pragma unroll
;     for (int j = 0; j < 2; ++j) epi(m0 + wm * 128 + i * 32 + 4 * (lane >> 5), n0 + wn * 64 + j * 32 + (lane & 31), acc[i][j]);
; }
.LBB0_195:
	ds_read_b128 v[170:173], v164 offset:36864
	ds_read_b128 v[180:183], v163 offset:36864
	ds_read_b128 v[184:187], v164 offset:36896
	ds_read_b128 v[188:191], v163 offset:36896
	ds_read_b128 v[192:195], v163 offset:41472
	ds_read_b128 v[196:199], v163 offset:41504
	s_andn2_b64 vcc, exec, s[6:7]
	s_waitcnt lgkmcnt(4)
	v_mfma_f32_32x32x16_bf16 v[112:127], v[170:173], v[180:183], v[112:127]
	s_waitcnt lgkmcnt(1)
	v_mfma_f32_32x32x16_bf16 v[96:111], v[170:173], v[192:195], v[96:111]
	ds_read_b128 v[170:173], v164 offset:41472
	ds_read_b128 v[200:203], v164 offset:41504
	s_waitcnt lgkmcnt(1)
	v_mfma_f32_32x32x16_bf16 v[80:95], v[170:173], v[180:183], v[80:95]
	v_mfma_f32_32x32x16_bf16 v[64:79], v[170:173], v[192:195], v[64:79]
	ds_read_b128 v[170:173], v164 offset:46080
	ds_read_b128 v[204:207], v164 offset:46112
	s_waitcnt lgkmcnt(1)
	v_mfma_f32_32x32x16_bf16 v[48:63], v[170:173], v[180:183], v[48:63]
	v_mfma_f32_32x32x16_bf16 v[32:47], v[170:173], v[192:195], v[32:47]
	ds_read_b128 v[170:173], v164 offset:50688
	ds_read_b128 v[210:213], v164 offset:50720
	s_waitcnt lgkmcnt(1)
	v_mfma_f32_32x32x16_bf16 v[16:31], v[170:173], v[180:183], v[16:31]
	v_mfma_f32_32x32x16_bf16 v[0:15], v[170:173], v[192:195], v[0:15]
	v_mfma_f32_32x32x16_bf16 v[112:127], v[184:187], v[188:191], v[112:127]
	v_mfma_f32_32x32x16_bf16 v[96:111], v[184:187], v[196:199], v[96:111]
	v_mfma_f32_32x32x16_bf16 v[80:95], v[200:203], v[188:191], v[80:95]
	v_mfma_f32_32x32x16_bf16 v[64:79], v[200:203], v[196:199], v[64:79]
	v_mfma_f32_32x32x16_bf16 v[48:63], v[204:207], v[188:191], v[48:63]
	v_mfma_f32_32x32x16_bf16 v[32:47], v[204:207], v[196:199], v[32:47]
	s_waitcnt lgkmcnt(0)
	v_mfma_f32_32x32x16_bf16 v[16:31], v[210:213], v[188:191], v[16:31]
	ds_read_b128 v[170:173], v164 offset:36928
	ds_read_b128 v[180:183], v163 offset:36928
	ds_read_b128 v[184:187], v164 offset:36960
	ds_read_b128 v[188:191], v163 offset:36960
	v_mfma_f32_32x32x16_bf16 v[0:15], v[210:213], v[196:199], v[0:15]
	ds_read_b128 v[192:195], v163 offset:41536
	ds_read_b128 v[196:199], v163 offset:41568
	s_waitcnt lgkmcnt(4)
	v_mfma_f32_32x32x16_bf16 v[112:127], v[170:173], v[180:183], v[112:127]
	s_waitcnt lgkmcnt(1)
	v_mfma_f32_32x32x16_bf16 v[96:111], v[170:173], v[192:195], v[96:111]
	ds_read_b128 v[170:173], v164 offset:41536
	ds_read_b128 v[200:203], v164 offset:41568
	s_waitcnt lgkmcnt(1)
	v_mfma_f32_32x32x16_bf16 v[80:95], v[170:173], v[180:183], v[80:95]
	v_mfma_f32_32x32x16_bf16 v[64:79], v[170:173], v[192:195], v[64:79]
	ds_read_b128 v[170:173], v164 offset:46144
	ds_read_b128 v[204:207], v164 offset:46176
	s_waitcnt lgkmcnt(1)
	v_mfma_f32_32x32x16_bf16 v[48:63], v[170:173], v[180:183], v[48:63]
	v_mfma_f32_32x32x16_bf16 v[32:47], v[170:173], v[192:195], v[32:47]
	ds_read_b128 v[170:173], v164 offset:50752
	ds_read_b128 v[210:213], v164 offset:50784
	s_waitcnt lgkmcnt(1)
	v_mfma_f32_32x32x16_bf16 v[16:31], v[170:173], v[180:183], v[16:31]
	v_mfma_f32_32x32x16_bf16 v[0:15], v[170:173], v[192:195], v[0:15]
	s_cbranch_vccnz .Lg2_b_plain
	s_waitcnt lgkmcnt(0)
	s_waitcnt vmcnt(7)
	ds_write_b128 v162, v[128:131]
	v_mfma_f32_32x32x16_bf16 v[112:127], v[184:187], v[188:191], v[112:127]
	s_waitcnt vmcnt(6)
	ds_write_b128 v162, v[132:135] offset:9216
	v_mfma_f32_32x32x16_bf16 v[96:111], v[184:187], v[196:199], v[96:111]
	s_waitcnt vmcnt(5)
	ds_write_b128 v162, v[136:139] offset:18432
	v_mfma_f32_32x32x16_bf16 v[80:95], v[200:203], v[188:191], v[80:95]
	s_waitcnt vmcnt(4)
	ds_write_b128 v162, v[140:143] offset:27648
	v_mfma_f32_32x32x16_bf16 v[64:79], v[200:203], v[196:199], v[64:79]
	s_waitcnt vmcnt(3)
	ds_write_b128 v178, v[144:147]
	v_mfma_f32_32x32x16_bf16 v[48:63], v[204:207], v[188:191], v[48:63]
	s_waitcnt vmcnt(2)
	ds_write_b128 v178, v[148:151] offset:9216
	v_mfma_f32_32x32x16_bf16 v[32:47], v[204:207], v[196:199], v[32:47]
	s_waitcnt vmcnt(1)
	ds_write_b128 v178, v[152:155] offset:18432
	v_mfma_f32_32x32x16_bf16 v[16:31], v[210:213], v[188:191], v[16:31]
	s_waitcnt vmcnt(0)
	ds_write_b128 v178, v[156:159] offset:27648
	v_mfma_f32_32x32x16_bf16 v[0:15], v[210:213], v[196:199], v[0:15]
	s_branch .LBB0_192
.Lg2_b_plain:
	v_mfma_f32_32x32x16_bf16 v[112:127], v[184:187], v[188:191], v[112:127]
	v_mfma_f32_32x32x16_bf16 v[96:111], v[184:187], v[196:199], v[96:111]
	v_mfma_f32_32x32x16_bf16 v[80:95], v[200:203], v[188:191], v[80:95]
	v_mfma_f32_32x32x16_bf16 v[64:79], v[200:203], v[196:199], v[64:79]
	v_mfma_f32_32x32x16_bf16 v[48:63], v[204:207], v[188:191], v[48:63]
	v_mfma_f32_32x32x16_bf16 v[32:47], v[204:207], v[196:199], v[32:47]
	s_waitcnt lgkmcnt(0)
	v_mfma_f32_32x32x16_bf16 v[16:31], v[210:213], v[188:191], v[16:31]
	v_mfma_f32_32x32x16_bf16 v[0:15], v[210:213], v[196:199], v[0:15]
	s_branch .LBB0_192
.LBB0_197:
	s_waitcnt vmcnt(0)
	v_and_b32_e32 v128, 0xc0, v174
	v_or_b32_e32 v132, s1, v128
	v_add_u32_e32 v129, s8, v177
	v_lshl_or_b32 v133, v176, 2, v129
	s_nop 0
	v_readfirstlane_b32 s6, v132
	s_nop 3
	s_cmpk_ge_u32 s6, 0xda0
	s_cbranch_scc1 .Lg2e_j0_skip
	s_mov_b64 s[10:11], s[56:57]
	s_movk_i32 s12, 0xe00
	s_mov_b32 s13, s6
	s_mov_b32 s14, 0
	s_cmpk_lt_u32 s6, 0x700
	s_cbranch_scc1 .Lg2e_j0_sel
	s_mov_b64 s[10:11], s[92:93]
	s_movk_i32 s12, 0x800
	s_sub_u32 s13, s6, 0x700
	s_mov_b32 s14, 1
	s_cmpk_lt_u32 s6, 0x900
	s_cbranch_scc1 .Lg2e_j0_sel
	s_mov_b64 s[10:11], s[62:63]
	s_movk_i32 s12, 0x540
	s_sub_u32 s13, s6, 0x900
	s_mov_b32 s14, 0
	s_cmpk_lt_u32 s6, 0xba0
	s_cbranch_scc1 .Lg2e_j0_sel
	s_mov_b64 s[10:11], s[92:93]
	s_movk_i32 s12, 0x800
	s_sub_u32 s13, s6, 0x9a0
	s_mov_b32 s14, 1
.Lg2e_j0_sel:
	s_cmp_eq_u32 s14, 0
	s_cbranch_scc1 .Lg2e_j0_go
	s_cmpk_ge_u32 s8, 0x4000
	s_cbranch_scc1 .Lg2e_j0_skip
.Lg2e_j0_go:
	s_mul_i32 s15, s12, 5
	v_add_lshl_u32 v134, v175, s13, 1
	v_add_u32_e32 v135, 0, v133
	v_mad_u32_u24 v136, v135, s12, v134
	v_cvt_pk_bf16_f32 v137, v112, v113
	global_store_short v136, v137, s[10:11]
	v_add_u32_e32 v138, s12, v136
	global_store_short_d16_hi v138, v137, s[10:11]
	v_cvt_pk_bf16_f32 v139, v114, v115
	v_add_u32_e32 v136, s12, v138
	global_store_short v136, v139, s[10:11]
	v_add_u32_e32 v138, s12, v136
	global_store_short_d16_hi v138, v139, s[10:11]
	v_cvt_pk_bf16_f32 v140, v116, v117
	v_add_u32_e32 v136, s15, v138
	global_store_short v136, v140, s[10:11]
	v_add_u32_e32 v138, s12, v136
	global_store_short_d16_hi v138, v140, s[10:11]
	v_cvt_pk_bf16_f32 v141, v118, v119
	v_add_u32_e32 v136, s12, v138
	global_store_short v136, v141, s[10:11]
	v_add_u32_e32 v138, s12, v136
	global_store_short_d16_hi v138, v141, s[10:11]
	v_cvt_pk_bf16_f32 v137, v120, v121
	v_add_u32_e32 v136, s15, v138
	global_store_short v136, v137, s[10:11]
	v_add_u32_e32 v138, s12, v136
	global_store_short_d16_hi v138, v137, s[10:11]
	v_cvt_pk_bf16_f32 v139, v122, v123
	v_add_u32_e32 v136, s12, v138
	global_store_short v136, v139, s[10:11]
	v_add_u32_e32 v138, s12, v136
	global_store_short_d16_hi v138, v139, s[10:11]
	v_cvt_pk_bf16_f32 v140, v124, v125
	v_add_u32_e32 v136, s15, v138
	global_store_short v136, v140, s[10:11]
	v_add_u32_e32 v138, s12, v136
	global_store_short_d16_hi v138, v140, s[10:11]
	v_cvt_pk_bf16_f32 v141, v126, v127
	v_add_u32_e32 v136, s12, v138
	global_store_short v136, v141, s[10:11]
	v_add_u32_e32 v138, s12, v136
	global_store_short_d16_hi v138, v141, s[10:11]
	v_add_u32_e32 v135, 32, v133
	v_mad_u32_u24 v136, v135, s12, v134
	v_cvt_pk_bf16_f32 v137, v80, v81
	global_store_short v136, v137, s[10:11]
	v_add_u32_e32 v138, s12, v136
	global_store_short_d16_hi v138, v137, s[10:11]
	v_cvt_pk_bf16_f32 v139, v82, v83
	v_add_u32_e32 v136, s12, v138
	global_store_short v136, v139, s[10:11]
	v_add_u32_e32 v138, s12, v136
	global_store_short_d16_hi v138, v139, s[10:11]
	v_cvt_pk_bf16_f32 v140, v84, v85
	v_add_u32_e32 v136, s15, v138
	global_store_short v136, v140, s[10:11]
	v_add_u32_e32 v138, s12, v136
	global_store_short_d16_hi v138, v140, s[10:11]
	v_cvt_pk_bf16_f32 v141, v86, v87
	v_add_u32_e32 v136, s12, v138
	global_store_short v136, v141, s[10:11]
	v_add_u32_e32 v138, s12, v136
	global_store_short_d16_hi v138, v141, s[10:11]
	v_cvt_pk_bf16_f32 v137, v88, v89
	v_add_u32_e32 v136, s15, v138
	global_store_short v136, v137, s[10:11]
	v_add_u32_e32 v138, s12, v136
	global_store_short_d16_hi v138, v137, s[10:11]
	v_cvt_pk_bf16_f32 v139, v90, v91
	v_add_u32_e32 v136, s12, v138
	global_store_short v136, v139, s[10:11]
	v_add_u32_e32 v138, s12, v136
	global_store_short_d16_hi v138, v139, s[10:11]
	v_cvt_pk_bf16_f32 v140, v92, v93
	v_add_u32_e32 v136, s15, v138
	global_store_short v136, v140, s[10:11]
	v_add_u32_e32 v138, s12, v136
	global_store_short_d16_hi v138, v140, s[10:11]
	v_cvt_pk_bf16_f32 v141, v94, v95
	v_add_u32_e32 v136, s12, v138
	global_store_short v136, v141, s[10:11]
	v_add_u32_e32 v138, s12, v136
	global_store_short_d16_hi v138, v141, s[10:11]
	v_add_u32_e32 v135, 64, v133
	v_mad_u32_u24 v136, v135, s12, v134
	v_cvt_pk_bf16_f32 v137, v48, v49
	global_store_short v136, v137, s[10:11]
	v_add_u32_e32 v138, s12, v136
	global_store_short_d16_hi v138, v137, s[10:11]
	v_cvt_pk_bf16_f32 v139, v50, v51
	v_add_u32_e32 v136, s12, v138
	global_store_short v136, v139, s[10:11]
	v_add_u32_e32 v138, s12, v136
	global_store_short_d16_hi v138, v139, s[10:11]
	v_cvt_pk_bf16_f32 v140, v52, v53
	v_add_u32_e32 v136, s15, v138
	global_store_short v136, v140, s[10:11]
	v_add_u32_e32 v138, s12, v136
	global_store_short_d16_hi v138, v140, s[10:11]
	v_cvt_pk_bf16_f32 v141, v54, v55
	v_add_u32_e32 v136, s12, v138
	global_store_short v136, v141, s[10:11]
	v_add_u32_e32 v138, s12, v136
	global_store_short_d16_hi v138, v141, s[10:11]
	v_cvt_pk_bf16_f32 v137, v56, v57
	v_add_u32_e32 v136, s15, v138
	global_store_short v136, v137, s[10:11]
	v_add_u32_e32 v138, s12, v136
	global_store_short_d16_hi v138, v137, s[10:11]
	v_cvt_pk_bf16_f32 v139, v58, v59
	v_add_u32_e32 v136, s12, v138
	global_store_short v136, v139, s[10:11]
	v_add_u32_e32 v138, s12, v136
	global_store_short_d16_hi v138, v139, s[10:11]
	v_cvt_pk_bf16_f32 v140, v60, v61
	v_add_u32_e32 v136, s15, v138
	global_store_short v136, v140, s[10:11]
	v_add_u32_e32 v138, s12, v136
	global_store_short_d16_hi v138, v140, s[10:11]
	v_cvt_pk_bf16_f32 v141, v62, v63
	v_add_u32_e32 v136, s12, v138
	global_store_short v136, v141, s[10:11]
	v_add_u32_e32 v138, s12, v136
	global_store_short_d16_hi v138, v141, s[10:11]
	v_add_u32_e32 v135, 96, v133
	v_mad_u32_u24 v136, v135, s12, v134
	v_cvt_pk_bf16_f32 v137, v16, v17
	global_store_short v136, v137, s[10:11]
	v_add_u32_e32 v138, s12, v136
	global_store_short_d16_hi v138, v137, s[10:11]
	v_cvt_pk_bf16_f32 v139, v18, v19
	v_add_u32_e32 v136, s12, v138
	global_store_short v136, v139, s[10:11]
	v_add_u32_e32 v138, s12, v136
	global_store_short_d16_hi v138, v139, s[10:11]
	v_cvt_pk_bf16_f32 v140, v20, v21
	v_add_u32_e32 v136, s15, v138
	global_store_short v136, v140, s[10:11]
	v_add_u32_e32 v138, s12, v136
	global_store_short_d16_hi v138, v140, s[10:11]
	v_cvt_pk_bf16_f32 v141, v22, v23
	v_add_u32_e32 v136, s12, v138
	global_store_short v136, v141, s[10:11]
	v_add_u32_e32 v138, s12, v136
	global_store_short_d16_hi v138, v141, s[10:11]
	v_cvt_pk_bf16_f32 v137, v24, v25
	v_add_u32_e32 v136, s15, v138
	global_store_short v136, v137, s[10:11]
	v_add_u32_e32 v138, s12, v136
	global_store_short_d16_hi v138, v137, s[10:11]
	v_cvt_pk_bf16_f32 v139, v26, v27
	v_add_u32_e32 v136, s12, v138
	global_store_short v136, v139, s[10:11]
	v_add_u32_e32 v138, s12, v136
	global_store_short_d16_hi v138, v139, s[10:11]
	v_cvt_pk_bf16_f32 v140, v28, v29
	v_add_u32_e32 v136, s15, v138
	global_store_short v136, v140, s[10:11]
	v_add_u32_e32 v138, s12, v136
	global_store_short_d16_hi v138, v140, s[10:11]
	v_cvt_pk_bf16_f32 v141, v30, v31
	v_add_u32_e32 v136, s12, v138
	global_store_short v136, v141, s[10:11]
	v_add_u32_e32 v138, s12, v136
	global_store_short_d16_hi v138, v141, s[10:11]
.Lg2e_j0_skip:
	s_add_u32 s6, s6, 32
	s_cmpk_ge_u32 s6, 0xda0
	s_cbranch_scc1 .Lg2e_j1_skip
	s_mov_b64 s[10:11], s[56:57]
	s_movk_i32 s12, 0xe00
	s_mov_b32 s13, s6
	s_mov_b32 s14, 0
	s_cmpk_lt_u32 s6, 0x700
	s_cbranch_scc1 .Lg2e_j1_sel
	s_mov_b64 s[10:11], s[92:93]
	s_movk_i32 s12, 0x800
	s_sub_u32 s13, s6, 0x700
	s_mov_b32 s14, 1
	s_cmpk_lt_u32 s6, 0x900
	s_cbranch_scc1 .Lg2e_j1_sel
	s_mov_b64 s[10:11], s[62:63]
	s_movk_i32 s12, 0x540
	s_sub_u32 s13, s6, 0x900
	s_mov_b32 s14, 0
	s_cmpk_lt_u32 s6, 0xba0
	s_cbranch_scc1 .Lg2e_j1_sel
	s_mov_b64 s[10:11], s[92:93]
	s_movk_i32 s12, 0x800
	s_sub_u32 s13, s6, 0x9a0
	s_mov_b32 s14, 1

; DI void phase2(const Params& P, unsigned char* lds) {
;     ...
;   for (int t = blockIdx.x; t < 66 * 14; t += gridDim.x) gemm_tile(g, (t / 14) * BM, (t % 14) * BN, lds, e);
.Lg2e_j1_go:
	s_mul_i32 s15, s12, 5
	v_add_lshl_u32 v134, v175, s13, 1
	v_add_u32_e32 v135, 0, v133
	v_mad_u32_u24 v136, v135, s12, v134
	v_cvt_pk_bf16_f32 v137, v96, v97
	global_store_short v136, v137, s[10:11]
	v_add_u32_e32 v138, s12, v136
	global_store_short_d16_hi v138, v137, s[10:11]
	v_cvt_pk_bf16_f32 v139, v98, v99
	v_add_u32_e32 v136, s12, v138
	global_store_short v136, v139, s[10:11]
	v_add_u32_e32 v138, s12, v136
	global_store_short_d16_hi v138, v139, s[10:11]
	v_cvt_pk_bf16_f32 v140, v100, v101
	v_add_u32_e32 v136, s15, v138
	global_store_short v136, v140, s[10:11]
	v_add_u32_e32 v138, s12, v136
	global_store_short_d16_hi v138, v140, s[10:11]
	v_cvt_pk_bf16_f32 v141, v102, v103
	v_add_u32_e32 v136, s12, v138
	global_store_short v136, v141, s[10:11]
	v_add_u32_e32 v138, s12, v136
	global_store_short_d16_hi v138, v141, s[10:11]
	v_cvt_pk_bf16_f32 v137, v104, v105
	v_add_u32_e32 v136, s15, v138
	global_store_short v136, v137, s[10:11]
	v_add_u32_e32 v138, s12, v136
	global_store_short_d16_hi v138, v137, s[10:11]
	v_cvt_pk_bf16_f32 v139, v106, v107
	v_add_u32_e32 v136, s12, v138
	global_store_short v136, v139, s[10:11]
	v_add_u32_e32 v138, s12, v136
	global_store_short_d16_hi v138, v139, s[10:11]
	v_cvt_pk_bf16_f32 v140, v108, v109
	v_add_u32_e32 v136, s15, v138
	global_store_short v136, v140, s[10:11]
	v_add_u32_e32 v138, s12, v136
	global_store_short_d16_hi v138, v140, s[10:11]
	v_cvt_pk_bf16_f32 v141, v110, v111
	v_add_u32_e32 v136, s12, v138
	global_store_short v136, v141, s[10:11]
	v_add_u32_e32 v138, s12, v136
	global_store_short_d16_hi v138, v141, s[10:11]
	v_add_u32_e32 v135, 32, v133
	v_mad_u32_u24 v136, v135, s12, v134
	v_cvt_pk_bf16_f32 v137, v64, v65
	global_store_short v136, v137, s[10:11]
	v_add_u32_e32 v138, s12, v136
	global_store_short_d16_hi v138, v137, s[10:11]
	v_cvt_pk_bf16_f32 v139, v66, v67
	v_add_u32_e32 v136, s12, v138
	global_store_short v136, v139, s[10:11]
	v_add_u32_e32 v138, s12, v136
	global_store_short_d16_hi v138, v139, s[10:11]
	v_cvt_pk_bf16_f32 v140, v68, v69
	v_add_u32_e32 v136, s15, v138
	global_store_short v136, v140, s[10:11]
	v_add_u32_e32 v138, s12, v136
	global_store_short_d16_hi v138, v140, s[10:11]
	v_cvt_pk_bf16_f32 v141, v70, v71
	v_add_u32_e32 v136, s12, v138
	global_store_short v136, v141, s[10:11]
	v_add_u32_e32 v138, s12, v136
	global_store_short_d16_hi v138, v141, s[10:11]
	v_cvt_pk_bf16_f32 v137, v72, v73
	v_add_u32_e32 v136, s15, v138
	global_store_short v136, v137, s[10:11]
	v_add_u32_e32 v138, s12, v136
	global_store_short_d16_hi v138, v137, s[10:11]
	v_cvt_pk_bf16_f32 v139, v74, v75
	v_add_u32_e32 v136, s12, v138
	global_store_short v136, v139, s[10:11]
	v_add_u32_e32 v138, s12, v136
	global_store_short_d16_hi v138, v139, s[10:11]
	v_cvt_pk_bf16_f32 v140, v76, v77
	v_add_u32_e32 v136, s15, v138
	global_store_short v136, v140, s[10:11]
	v_add_u32_e32 v138, s12, v136
	global_store_short_d16_hi v138, v140, s[10:11]
	v_cvt_pk_bf16_f32 v141, v78, v79
	v_add_u32_e32 v136, s12, v138
	global_store_short v136, v141, s[10:11]
	v_add_u32_e32 v138, s12, v136
	global_store_short_d16_hi v138, v141, s[10:11]
	v_add_u32_e32 v135, 64, v133
	v_mad_u32_u24 v136, v135, s12, v134
	v_cvt_pk_bf16_f32 v137, v32, v33
	global_store_short v136, v137, s[10:11]
	v_add_u32_e32 v138, s12, v136
	global_store_short_d16_hi v138, v137, s[10:11]
	v_cvt_pk_bf16_f32 v139, v34, v35
	v_add_u32_e32 v136, s12, v138
	global_store_short v136, v139, s[10:11]
	v_add_u32_e32 v138, s12, v136
	global_store_short_d16_hi v138, v139, s[10:11]
	v_cvt_pk_bf16_f32 v140, v36, v37
	v_add_u32_e32 v136, s15, v138
	global_store_short v136, v140, s[10:11]
	v_add_u32_e32 v138, s12, v136
	global_store_short_d16_hi v138, v140, s[10:11]
	v_cvt_pk_bf16_f32 v141, v38, v39
	v_add_u32_e32 v136, s12, v138
	global_store_short v136, v141, s[10:11]
	v_add_u32_e32 v138, s12, v136
	global_store_short_d16_hi v138, v141, s[10:11]
	v_cvt_pk_bf16_f32 v137, v40, v41
	v_add_u32_e32 v136, s15, v138
	global_store_short v136, v137, s[10:11]
	v_add_u32_e32 v138, s12, v136
	global_store_short_d16_hi v138, v137, s[10:11]
	v_cvt_pk_bf16_f32 v139, v42, v43
	v_add_u32_e32 v136, s12, v138
	global_store_short v136, v139, s[10:11]
	v_add_u32_e32 v138, s12, v136
	global_store_short_d16_hi v138, v139, s[10:11]
	v_cvt_pk_bf16_f32 v140, v44, v45
	v_add_u32_e32 v136, s15, v138
	global_store_short v136, v140, s[10:11]
	v_add_u32_e32 v138, s12, v136
	global_store_short_d16_hi v138, v140, s[10:11]
	v_cvt_pk_bf16_f32 v141, v46, v47
	v_add_u32_e32 v136, s12, v138
	global_store_short v136, v141, s[10:11]
	v_add_u32_e32 v138, s12, v136
	global_store_short_d16_hi v138, v141, s[10:11]
	v_add_u32_e32 v135, 96, v133
	v_mad_u32_u24 v136, v135, s12, v134
	v_cvt_pk_bf16_f32 v137, v0, v1
	global_store_short v136, v137, s[10:11]
	v_add_u32_e32 v138, s12, v136
	global_store_short_d16_hi v138, v137, s[10:11]
	v_cvt_pk_bf16_f32 v139, v2, v3
	v_add_u32_e32 v136, s12, v138
	global_store_short v136, v139, s[10:11]
	v_add_u32_e32 v138, s12, v136
	global_store_short_d16_hi v138, v139, s[10:11]
	v_cvt_pk_bf16_f32 v140, v4, v5
	v_add_u32_e32 v136, s15, v138
	global_store_short v136, v140, s[10:11]
	v_add_u32_e32 v138, s12, v136
	global_store_short_d16_hi v138, v140, s[10:11]
	v_cvt_pk_bf16_f32 v141, v6, v7
	v_add_u32_e32 v136, s12, v138
	global_store_short v136, v141, s[10:11]
	v_add_u32_e32 v138, s12, v136
	global_store_short_d16_hi v138, v141, s[10:11]
	v_cvt_pk_bf16_f32 v137, v8, v9
	v_add_u32_e32 v136, s15, v138
	global_store_short v136, v137, s[10:11]
	v_add_u32_e32 v138, s12, v136
	global_store_short_d16_hi v138, v137, s[10:11]
	v_cvt_pk_bf16_f32 v139, v10, v11
	v_add_u32_e32 v136, s12, v138
	global_store_short v136, v139, s[10:11]
	v_add_u32_e32 v138, s12, v136
	global_store_short_d16_hi v138, v139, s[10:11]
	v_cvt_pk_bf16_f32 v140, v12, v13
	v_add_u32_e32 v136, s15, v138
	global_store_short v136, v140, s[10:11]
	v_add_u32_e32 v138, s12, v136
	global_store_short_d16_hi v138, v140, s[10:11]
	v_cvt_pk_bf16_f32 v141, v14, v15
	v_add_u32_e32 v136, s12, v138
	global_store_short v136, v141, s[10:11]
	v_add_u32_e32 v138, s12, v136
	global_store_short_d16_hi v138, v141, s[10:11]
.Lg2e_j1_skip:
	s_mov_b64 s[4:5], -1
	s_branch .LBB0_190
